# v76: v68 + early L2 write-back at the group-wide seams issued on arrival by two follower workgroups per XCD (lq 40 and 56, which arrive early), so the final write-back has less to flush
# speedup vs baseline: 1.0092x; 1.0092x over previous
.LBB0_415:
	s_getreg_b32 s2, hwreg(HW_REG_XCC_ID, 0, 4)
	s_waitcnt vmcnt(0)
	s_waitcnt lgkmcnt(0)
	s_barrier
	s_and_saveexec_b64 s[0:1], s[14:15]
	s_cbranch_execz .LBB0_467
	v_readlane_b32 s98, v255, 63
	s_nop 0
	s_cmp_lg_u32 s98, 0
	s_cbranch_scc1 .Lhb_full_g1
	s_cmp_lg_u32 s33, 64
	s_cbranch_scc1 .Lhb_full_g1
	buffer_inv sc1
	v_readlane_b32 s98, v255, 56
	v_readlane_b32 s100, v253, 1
	v_readlane_b32 s101, v253, 2
	v_readlane_b32 s99, v253, 0
	v_readlane_b32 vcc_lo, v254, 28
	s_add_i32 s98, s98, 1
	v_writelane_b32 v255, s98, 56
	s_lshl_b32 s99, s99, 14
	s_sub_u32 s100, s100, s99
	s_subb_u32 s101, s101, 0
	s_add_u32 s100, s100, 0xb000
	s_addc_u32 s101, s101, 0
	s_getreg_b32 s99, hwreg(HW_REG_XCC_ID, 0, 4)
	s_and_b32 s99, s99, 15
	s_lshl_b32 s99, s99, 8
	s_lshl_b32 vcc_hi, vcc_lo, 2
	s_add_i32 vcc_hi, vcc_hi, s99
	v_mov_b32_e32 v4, vcc_hi
	v_mov_b32_e32 v5, s98
	global_store_dword v4, v5, s[100:101]
	s_cmp_eq_u32 vcc_lo, 0
	s_cbranch_scc1 .Lhb_lead_g1
	s_and_b32 vcc_hi, vcc_lo, 47
	s_cmp_lg_u32 vcc_hi, 40
	s_cbranch_scc1 .Lhb_noewb_g1
	buffer_wbl2 sc1
.Lhb_noewb_g1:
	s_lshr_b32 s99, s99, 2
	v_mov_b32_e32 v4, s99
	s_mov_b32 s99, 0

.LBB0_574:
	s_getreg_b32 s2, hwreg(HW_REG_XCC_ID, 0, 4)
	s_waitcnt vmcnt(0)
	s_barrier
	s_and_saveexec_b64 s[0:1], s[14:15]
	v_readlane_b32 s34, v254, 58
	v_readlane_b32 s35, v254, 59
	s_cbranch_execz .LBB0_626
	v_readlane_b32 s98, v255, 63
	s_nop 0
	s_cmp_lg_u32 s98, 0
	s_cbranch_scc1 .Lhb_full_mix
	s_cmp_lg_u32 s33, 64
	s_cbranch_scc1 .Lhb_full_mix
	v_readlane_b32 s98, v255, 56
	v_readlane_b32 s100, v253, 1
	v_readlane_b32 s101, v253, 2
	v_readlane_b32 s99, v253, 0
	v_readlane_b32 vcc_lo, v254, 28
	s_add_i32 s98, s98, 1
	v_writelane_b32 v255, s98, 56
	s_lshl_b32 s99, s99, 14
	s_sub_u32 s100, s100, s99
	s_subb_u32 s101, s101, 0
	s_add_u32 s100, s100, 0xb000
	s_addc_u32 s101, s101, 0
	s_getreg_b32 s99, hwreg(HW_REG_XCC_ID, 0, 4)
	s_and_b32 s99, s99, 15
	s_lshl_b32 s99, s99, 8
	s_lshl_b32 vcc_hi, vcc_lo, 2
	s_add_i32 vcc_hi, vcc_hi, s99
	v_mov_b32_e32 v4, vcc_hi
	v_mov_b32_e32 v5, s98
	global_store_dword v4, v5, s[100:101]
	s_cmp_eq_u32 vcc_lo, 0
	s_cbranch_scc1 .Lhb_lead_mix
	s_and_b32 vcc_hi, vcc_lo, 47
	s_cmp_lg_u32 vcc_hi, 40
	s_cbranch_scc1 .Lhb_noewb_mix
	buffer_wbl2 sc1
